# v10 + barrier arrival: the two integer divisions replaced by a per-workgroup round counter
# speedup vs baseline: 1.0048x; 1.0041x over previous
; #define LAS __attribute__((address_space(3)))
; __device__ __forceinline__ unsigned xb_ld(unsigned* p)              { return __hip_atomic_load(p, __ATOMIC_RELAXED, __HIP_MEMORY_SCOPE_AGENT); }
; __device__ __forceinline__ unsigned xb_add(unsigned* p, unsigned v) { return __hip_atomic_fetch_add(p, v, __ATOMIC_RELAXED, __HIP_MEMORY_SCOPE_AGENT); }
; __device__ __forceinline__ unsigned xb_xcc_id() { return (unsigned)__builtin_amdgcn_s_getreg((3 << 11) | 20) & 0xFu; }
; __device__ __forceinline__ XcdBarrier xcd_barrier_post(unsigned* bar, volatile LAS unsigned* st) {
;     XcdBarrier b; b.bar = bar; b.x = xb_xcc_id(); b.st = st;
;     if (threadIdx.x == 0) (void)xb_add(&bar[XB_XCNT(b.x)], 1u);
;     return b;
; }
; __device__ __forceinline__ void xcd_barrier_complete(unsigned* bar, unsigned x, unsigned& nloc, unsigned& nx) {
;     const unsigned G = gridDim.x * gridDim.y * gridDim.z;
;     unsigned sum, cnt, mine, sp = 0u;
;     for (;;) {
;         sum = 0u; cnt = 0u; mine = 0u;
; #pragma unroll
;         for (unsigned j = 0; j < 16; ++j) { const unsigned c = xb_ld(&bar[XB_XCNT(j)]); sum += c; cnt += (c > 0u) ? 1u : 0u; mine = (j == x) ? c : mine; }
;         if (sum == G) break;
;         __builtin_amdgcn_s_sleep(1);
;         if ((++sp & 255u) == 0u) { if (xb_ld(&bar[XB_TMO])) break; if (sp > XB_SPIN_CAP) { atomicAdd(&bar[XB_TMO], 1u); break; } }
;     }
;     nloc = mine > 0u ? mine : 1u; nx = cnt > 0u ? cnt : 1u;
; }
; __global__ void __launch_bounds__(NTHREADS, 2) fwd(Args a) {
;     ...
;     const int G = gridDim.x, bx = blockIdx.x;
;     volatile LAS unsigned* bst = (volatile LAS unsigned*)(lds + LDS_BYTES - 16);
;     if (threadIdx.x < 2) bst[threadIdx.x] = 0u;
;     __syncthreads();
;     XcdBarrier xbar = xcd_barrier_post((unsigned*)(a.ws + WS_BAR), bst);
.LBB0_6:
	s_load_dwordx16 s[36:51], s[0:1], 0xc0
	s_mov_b32 s57, s28
	s_mov_b32 s98, 0
	s_nop 0
	v_writelane_b32 v255, s98, 37
	v_mbcnt_lo_u32_b32 v2, -1, 0
	v_mbcnt_hi_u32_b32 v227, -1, v2
	v_and_b32_e32 v2, 64, v227
	s_waitcnt lgkmcnt(0)
	s_add_u32 s6, s50, 0x5c40200
	s_addc_u32 s7, s51, 0
	v_writelane_b32 v251, s6, 20
	v_mov_b32_e32 v207, 0
	v_mov_b32_e32 v222, 0x358637bd
	v_writelane_b32 v251, s7, 21
	s_add_u32 s6, s50, 0x5c40400
	s_addc_u32 s7, s51, 0
	v_writelane_b32 v251, s6, 22
	v_add_u32_e32 v229, 64, v2
	v_xor_b32_e32 v234, 16, v227
	v_writelane_b32 v251, s7, 23
	s_add_u32 s6, s50, 0x5c40500
	s_addc_u32 s7, s51, 0
	v_writelane_b32 v251, s6, 24
	v_mov_b32_e32 v235, 0x3727c5ac
	s_movk_i32 s53, 0x1000
	v_writelane_b32 v251, s7, 25
	s_add_u32 s6, s50, 0x5c40600
	s_addc_u32 s7, s51, 0
	v_writelane_b32 v251, s6, 26
	s_mov_b32 s26, 0x1e000
	s_movk_i32 s27, 0x7fff
	v_writelane_b32 v251, s7, 27
	s_add_u32 s6, s50, 0x5c40700
	s_addc_u32 s7, s51, 0
	v_writelane_b32 v251, s6, 28
	s_mov_b32 s33, 0x60000
	s_mov_b32 s30, 0xa8000
	v_writelane_b32 v251, s7, 29
	s_add_u32 s6, s50, 0x5c40800
	s_addc_u32 s7, s51, 0
	v_writelane_b32 v251, s6, 30
	s_mov_b32 s31, 0x6c000
	s_movk_i32 s24, 0xe00
	v_writelane_b32 v251, s7, 31
	s_add_u32 s6, s50, 0x5c40900
	s_addc_u32 s7, s51, 0
	v_writelane_b32 v251, s6, 32
	s_movk_i32 s55, 0x210
	s_movk_i32 s25, 0x13c0
	v_writelane_b32 v251, s7, 33
	s_add_u32 s6, s50, 0x5c40a00
	s_addc_u32 s7, s51, 0
	v_writelane_b32 v251, s6, 34
	s_nop 1
	v_writelane_b32 v251, s7, 35
	s_add_u32 s6, s50, 0x5c40b00
	s_addc_u32 s7, s51, 0
	v_writelane_b32 v251, s6, 36
	s_nop 1
	v_writelane_b32 v251, s7, 37
	s_add_u32 s6, s50, 0x5c40c00
	s_addc_u32 s7, s51, 0
	v_writelane_b32 v251, s6, 38
	s_nop 1
	v_writelane_b32 v251, s7, 39
	s_add_u32 s6, s50, 0x5c40d00
	s_addc_u32 s7, s51, 0
	v_writelane_b32 v251, s6, 40
	s_nop 1
	v_writelane_b32 v251, s7, 41
	s_add_u32 s6, s50, 0x5c40e00
	s_addc_u32 s7, s51, 0
	v_writelane_b32 v251, s6, 42
	s_nop 1
	v_writelane_b32 v251, s7, 43
	s_add_u32 s6, s50, 0x5c40f00
	s_addc_u32 s7, s51, 0
	v_writelane_b32 v251, s6, 44
	s_nop 1
	v_writelane_b32 v251, s7, 45
	s_add_u32 s6, s50, 0x5c41000
	s_addc_u32 s7, s51, 0
	v_writelane_b32 v251, s6, 46
	s_nop 1
	v_writelane_b32 v251, s7, 47
	s_add_u32 s6, s50, 0x5c41100
	s_addc_u32 s7, s51, 0
	v_writelane_b32 v251, s6, 48
	s_nop 1
	v_writelane_b32 v251, s7, 49
	s_add_u32 s6, s50, 0x5c41200
	s_addc_u32 s7, s51, 0
	v_writelane_b32 v251, s6, 50
	s_nop 1
	v_writelane_b32 v251, s7, 51
	s_add_u32 s6, s50, 0x5c41300
	s_addc_u32 s7, s51, 0
	v_writelane_b32 v251, s6, 52
	s_cmp_eq_u32 s2, 15
	s_nop 0
	v_writelane_b32 v251, s7, 53
	s_cselect_b64 s[6:7], -1, 0
	v_writelane_b32 v251, s6, 54
	s_cmp_eq_u32 s2, 14
	s_nop 0
	v_writelane_b32 v251, s7, 55
	s_cselect_b64 s[6:7], -1, 0
	v_writelane_b32 v251, s6, 56
	s_cmp_eq_u32 s2, 13
	s_nop 0
	v_writelane_b32 v251, s7, 57
	s_cselect_b64 s[6:7], -1, 0
	v_writelane_b32 v251, s6, 58
	s_cmp_eq_u32 s2, 12
	s_nop 0
	v_writelane_b32 v251, s7, 59
	s_cselect_b64 s[6:7], -1, 0
	v_writelane_b32 v251, s6, 60
	s_cmp_eq_u32 s2, 11
	s_nop 0
	v_writelane_b32 v251, s7, 61
	s_cselect_b64 s[6:7], -1, 0
	v_writelane_b32 v251, s6, 62
	s_cmp_eq_u32 s2, 10
	s_nop 0
	v_writelane_b32 v251, s7, 63
	s_cselect_b64 s[6:7], -1, 0
	v_writelane_b32 v252, s6, 0
	s_cmp_eq_u32 s2, 9
	s_nop 0
	v_writelane_b32 v252, s7, 1
	s_cselect_b64 s[6:7], -1, 0
	v_writelane_b32 v252, s6, 2
	s_cmp_eq_u32 s2, 8
	s_nop 0
	v_writelane_b32 v252, s7, 3
	s_cselect_b64 s[6:7], -1, 0
	v_writelane_b32 v252, s6, 4
	s_cmp_eq_u32 s2, 7
	s_nop 0
	v_writelane_b32 v252, s7, 5
	s_cselect_b64 s[6:7], -1, 0
	v_writelane_b32 v252, s6, 6
	s_cmp_eq_u32 s2, 6
	s_nop 0
	v_writelane_b32 v252, s7, 7
	s_cselect_b64 s[6:7], -1, 0
	v_writelane_b32 v252, s6, 8
	s_cmp_eq_u32 s2, 5
	s_nop 0
	v_writelane_b32 v252, s7, 9
	s_cselect_b64 s[6:7], -1, 0
	v_writelane_b32 v252, s6, 10
	s_cmp_eq_u32 s2, 4
	s_nop 0
	v_writelane_b32 v252, s7, 11
	s_cselect_b64 s[6:7], -1, 0
	v_writelane_b32 v252, s6, 12
	s_cmp_eq_u32 s2, 3
	s_nop 0
	v_writelane_b32 v252, s7, 13
	s_cselect_b64 s[6:7], -1, 0
	v_writelane_b32 v252, s6, 14
	s_cmp_eq_u32 s2, 2
	s_nop 0
	v_writelane_b32 v252, s7, 15
	s_cselect_b64 s[6:7], -1, 0
	v_writelane_b32 v252, s6, 16
	s_cmp_eq_u32 s2, 1
	s_nop 0
	v_writelane_b32 v252, s7, 17
	s_cselect_b64 s[6:7], -1, 0
	v_writelane_b32 v252, s6, 18
	s_cmp_eq_u32 s2, 0
	s_nop 0
	v_writelane_b32 v252, s7, 19
	s_cselect_b64 s[6:7], -1, 0
	s_lshl_b32 s2, s2, 8
	s_add_u32 s2, s4, s2
	s_addc_u32 s3, s5, 0
	v_writelane_b32 v252, s6, 20
	s_add_u32 s4, s2, 0x1400
	s_addc_u32 s5, s3, 0
	v_writelane_b32 v252, s7, 21
	v_writelane_b32 v252, s4, 22
	s_add_u32 s2, s2, 0x2400
	s_addc_u32 s3, s3, 0
	v_writelane_b32 v252, s5, 23
	v_writelane_b32 v252, s2, 24
	s_nop 1
	v_writelane_b32 v252, s3, 25
	s_add_u32 s2, s50, 0x5c43400
	s_addc_u32 s3, s51, 0
	v_writelane_b32 v252, s2, 26
	s_nop 1
	v_writelane_b32 v252, s3, 27
	s_add_u32 s2, s50, 0x5c43500
	s_addc_u32 s3, s51, 0
	s_lshl_b32 s6, s97, 3
	s_lshl_b32 s96, s95, 3
	s_add_u32 s92, s50, 0xa100000
	v_writelane_b32 v252, s2, 28
	s_addc_u32 s93, s51, 0
	s_lshl_b32 s8, s95, 4
	v_writelane_b32 v252, s3, 29
	s_add_u32 s2, s50, 0x5c50000
	s_addc_u32 s3, s51, 0
	v_writelane_b32 v252, s2, 30
	s_lshl_b32 s10, s95, 9
	s_nop 0
	v_writelane_b32 v252, s3, 31
	s_lshl_b32 s2, s97, 9
	v_writelane_b32 v252, s2, 32
	s_add_u32 s2, s50, 0x400000
	s_addc_u32 s3, s51, 0
	v_writelane_b32 v252, s2, 33
	s_nop 1
	v_writelane_b32 v252, s3, 34
	s_add_u32 s2, s50, 0x100000
	s_addc_u32 s3, s51, 0
	v_writelane_b32 v252, s2, 35
	s_nop 1
	v_writelane_b32 v252, s3, 36
	s_add_u32 s2, s50, 0xc0000
	s_addc_u32 s3, s51, 0
;     __device__ bool next(int i, Unit& u) const {
;         long L = (long)i * G + c;
;         u.k0 = 0; u.nt = KT; u.S = 0; u.ks = 0; u.slot = 0;
;         if (L < nwg) {
;             int wgid = (int)L; { const int q = nwg / NXCD, r = nwg % NXCD, xcd = wgid % NXCD, off = wgid / NXCD; wgid = (xcd < r ? xcd * (q + 1) : r * (q + 1) + (xcd - r) * q) + off; }
;             const int nig = WGM * nN, gid = wgid / nig, fm = gid * WGM, gsz = (nM - fm) < WGM ? (nM - fm) : WGM;
;             u.pm = fm + ((wgid % nig) % gsz); u.pn = (wgid % nig) / gsz; return true;
; __global__ void __launch_bounds__(NTHREADS, 2) fwd(Args a) {
;     ...
;                 const int first = (G == 256) ? 128 : 0;
	v_writelane_b32 v252, s2, 37
	s_nop 1
	v_writelane_b32 v252, s3, 38
	s_add_u32 s2, s50, 0x280000
	s_addc_u32 s3, s51, 0
	v_writelane_b32 v252, s2, 39
	s_cmpk_lt_i32 s97, 0xc0
	s_nop 0
	v_writelane_b32 v252, s3, 40
	s_cselect_b64 s[2:3], -1, 0
	v_writelane_b32 v252, s2, 41
	s_nop 1
	v_writelane_b32 v252, s3, 42
	s_add_u32 s2, s50, 0x5b00000
	s_addc_u32 s3, s51, 0
	v_writelane_b32 v252, s2, 43
	s_nop 1
	v_writelane_b32 v252, s3, 44
	s_add_u32 s2, s50, 0x5b80000
	v_writelane_b32 v252, s2, 45
	s_addc_u32 s2, s51, 0
	v_writelane_b32 v252, s2, 46
	s_add_u32 s2, s50, 0x5c00000
	s_addc_u32 s3, s51, 0
	v_writelane_b32 v252, s2, 47
	s_nop 1
	v_writelane_b32 v252, s3, 48
	s_add_u32 s2, s50, 0x14e00000
	s_addc_u32 s3, s51, 0
	s_add_u32 s58, s50, 0xc300000
	v_writelane_b32 v252, s2, 49
	s_addc_u32 s59, s51, 0
	s_ashr_i32 s94, s97, 31
	v_writelane_b32 v252, s3, 50
	s_lshr_b32 s2, s94, 29
	s_add_i32 s2, s97, s2
	s_ashr_i32 s5, s2, 3
	s_and_b32 s2, s2, -8
	s_sub_i32 s7, s97, s2
	s_ashr_i32 s3, s95, 31
	s_add_u32 s12, s95, s97
	s_addc_u32 s13, s3, s94
	s_ashr_i32 s2, s12, 31
	s_lshr_b32 s2, s2, 29
	s_add_i32 s2, s12, s2
	s_ashr_i32 s4, s2, 3
	s_and_b32 s2, s2, -8
	s_sub_i32 s2, s12, s2
	v_writelane_b32 v252, s4, 51
	s_cmp_lt_i32 s2, 0
	v_writelane_b32 v252, s2, 52
	s_cselect_b64 s[14:15], -1, 0
	v_writelane_b32 v252, s14, 53
	s_nop 1
	v_writelane_b32 v252, s15, 54
	s_add_u32 s14, s12, s95
	v_writelane_b32 v252, s12, 55
	s_addc_u32 s15, s13, s3
	s_ashr_i32 s2, s14, 31
	s_lshr_b32 s2, s2, 29
	s_add_i32 s2, s14, s2
	s_ashr_i32 s4, s2, 3
	s_and_b32 s2, s2, -8
	v_writelane_b32 v252, s13, 56
	s_sub_i32 s2, s14, s2
	v_writelane_b32 v252, s4, 57
	s_cmp_lt_i32 s2, 0
	v_writelane_b32 v252, s2, 58
	s_cselect_b64 s[12:13], -1, 0
	v_writelane_b32 v252, s12, 59
	s_nop 1
	v_writelane_b32 v252, s13, 60
	s_add_u32 s12, s14, s95
	v_writelane_b32 v252, s14, 61
	s_addc_u32 s13, s15, s3
	s_ashr_i32 s2, s12, 31
	s_lshr_b32 s2, s2, 29
	s_add_i32 s2, s12, s2
	s_ashr_i32 s4, s2, 3
	s_and_b32 s2, s2, -8
	s_sub_i32 s2, s12, s2
	s_cmp_lt_i32 s2, 0
	v_writelane_b32 v252, s15, 62
	v_writelane_b32 v253, s2, 0
	s_cselect_b64 s[14:15], -1, 0
	v_writelane_b32 v253, s14, 1
	v_writelane_b32 v252, s4, 63
	s_nop 0
	v_writelane_b32 v253, s15, 2
	s_add_u32 s14, s12, s95
	v_writelane_b32 v253, s12, 3
	s_addc_u32 s15, s13, s3
	s_ashr_i32 s2, s14, 31
	s_lshr_b32 s2, s2, 29
	s_add_i32 s2, s14, s2
	s_ashr_i32 s4, s2, 3
	s_and_b32 s2, s2, -8
	v_writelane_b32 v253, s13, 4
	s_sub_i32 s2, s14, s2
	v_writelane_b32 v253, s4, 5
	s_cmp_lt_i32 s2, 0
	v_writelane_b32 v253, s2, 6
	s_cselect_b64 s[12:13], -1, 0
	v_writelane_b32 v253, s12, 7
	s_nop 1
	v_writelane_b32 v253, s13, 8
	s_add_u32 s12, s14, s95
	v_writelane_b32 v253, s3, 9
	v_writelane_b32 v253, s14, 10
	s_addc_u32 s13, s15, s3
	s_ashr_i32 s2, s12, 31
	s_lshr_b32 s2, s2, 29
	s_add_i32 s2, s12, s2
	v_writelane_b32 v253, s15, 11
	s_ashr_i32 s3, s2, 3
	v_writelane_b32 v253, s3, 12
	s_and_b32 s2, s2, -8
	v_writelane_b32 v253, s12, 13
	s_sub_i32 s2, s12, s2
	s_cmp_lt_i32 s2, 0
	v_writelane_b32 v253, s13, 14
	v_writelane_b32 v253, s2, 15
	s_cselect_b64 s[2:3], -1, 0
	v_writelane_b32 v253, s2, 16
	s_mov_b32 s13, 0
	s_mov_b32 s15, s13
	v_writelane_b32 v253, s3, 17
	s_add_u32 s2, s50, 0xff00000
	s_addc_u32 s3, s51, 0
	v_writelane_b32 v253, s2, 18
	s_cmpk_gt_i32 s97, 0xff
	s_nop 0
	v_writelane_b32 v253, s3, 19
	s_cselect_b64 s[2:3], -1, 0
	v_writelane_b32 v253, s2, 20
	s_nop 1
	v_writelane_b32 v253, s3, 21
	s_add_u32 s2, s97, 0xffffff00
	s_addc_u32 s3, 0, -1
	v_writelane_b32 v253, s2, 22
	s_lshl_b32 s4, s7, 5
	s_bfe_u32 s9, s97, 0x20003
	v_writelane_b32 v253, s3, 23
	s_lshr_b32 s2, s97, 2
	s_bfe_u32 s2, s2, 0x40002
	s_or_b32 s2, s2, 64
	v_writelane_b32 v253, s2, 24
	s_lshr_b32 s2, s97, 3
	s_bfe_u32 s2, s2, 0x30002
	s_or_b32 s2, s2, 64
	v_writelane_b32 v253, s2, 25
	s_bfe_u32 s2, s97, 0x60002
	v_writelane_b32 v253, s2, 26
	s_bfe_u32 s3, s97, 0x20002
	v_writelane_b32 v253, s3, 27
	s_bfe_u32 s3, s97, 0x50003
	s_and_b32 s2, s97, 3
	v_writelane_b32 v253, s3, 28
	s_and_b32 s3, s97, 7
	s_lshl_b32 s12, s2, 17
	s_lshl_b32 s14, s3, 18
	v_writelane_b32 v253, s9, 29
	s_cmpk_eq_i32 s95, 0x100
	v_writelane_b32 v253, s2, 30
	s_cselect_b32 s2, 0x80, 0
	s_cmp_ge_i32 s97, s2
	v_writelane_b32 v253, s3, 31
	s_cselect_b64 s[16:17], -1, 0
	s_sub_i32 s3, s97, s2
	v_writelane_b32 v253, s16, 32
	s_lshl_b32 s3, s3, 3
	s_sub_i32 s2, s95, s2
	v_writelane_b32 v253, s17, 33
	s_addk_i32 s3, 0x1700
	v_writelane_b32 v253, s3, 34
	s_lshl_b32 s3, s2, 3
	v_writelane_b32 v253, s3, 35
	s_lshl_b32 s2, s2, 4
	v_writelane_b32 v253, s2, 36
	s_add_u32 s2, s50, 0x5c43700
	v_writelane_b32 v253, s2, 37
	s_addc_u32 s2, s51, 0
	v_writelane_b32 v253, s2, 38
	s_add_u32 s2, s50, 0xc300800
	s_addc_u32 s3, s51, 0
	v_writelane_b32 v253, s2, 39
	s_nop 1
	v_writelane_b32 v253, s3, 40
	s_add_u32 s2, s50, 0xc300600
	s_addc_u32 s3, s51, 0
	v_writelane_b32 v253, s2, 41
	s_nop 1
	v_writelane_b32 v253, s3, 42
	s_add_u32 s2, s50, 0x180000
	s_addc_u32 s3, s51, 0
	v_writelane_b32 v253, s2, 43
	s_nop 1
	v_writelane_b32 v253, s3, 44
	s_add_u32 s2, s50, 0xc300200
	s_addc_u32 s3, s51, 0
;     __device__ bool next(int i, Unit& u) const {
;     ...
;             int wgid = (int)L; { const int q = nwg / NXCD, r = nwg % NXCD, xcd = wgid % NXCD, off = wgid / NXCD; wgid = (xcd < r ? xcd * (q + 1) : r * (q + 1) + (xcd - r) * q) + off; }
;             const int nig = WGM * nN, gid = wgid / nig, fm = gid * WGM, gsz = (nM - fm) < WGM ? (nM - fm) : WGM;
;             u.pm = fm + ((wgid % nig) % gsz); u.pn = (wgid % nig) / gsz; return true;
; __global__ void __launch_bounds__(NTHREADS, 2) fwd(Args a) {
;     ...
;                 const int nwg = 68 * 16, extra = nwg % G, first = extra ? extra : 0;
	v_writelane_b32 v253, s2, 45
	s_cmp_lt_i32 s7, 0
	s_nop 0
	v_writelane_b32 v253, s3, 46
	s_cselect_b64 s[2:3], -1, 0
	v_writelane_b32 v253, s2, 47
	s_nop 1
	v_writelane_b32 v253, s3, 48
	s_and_b64 s[2:3], s[2:3], exec
	s_mul_i32 s2, s7, 33
	s_cselect_b32 s2, s2, s4
	s_add_i32 s2, s2, s5
	s_ashr_i32 s3, s2, 31
	s_lshr_b32 s3, s3, 27
	s_add_i32 s3, s2, s3
	s_and_b32 s4, s3, 0xffe0
	s_sub_i32 s2, s2, s4
	s_bfe_i32 s4, s2, 0x80000
	s_bfe_u32 s4, s4, 0x3000c
	v_writelane_b32 v253, s7, 49
	s_add_i32 s4, s2, s4
	v_writelane_b32 v253, s5, 50
	s_and_b32 s5, s4, 0xf8
	s_sub_i32 s2, s2, s5
	s_ashr_i32 s3, s3, 5
	s_lshl_b32 s3, s3, 3
	s_sext_i32_i8 s2, s2
	s_add_i32 s2, s3, s2
	v_writelane_b32 v253, s2, 51
	s_abs_i32 s2, s95
	v_cvt_f32_u32_e32 v1, s2
	s_sub_i32 s3, 0, s2
	s_movk_i32 s7, 0x6000
	v_rcp_iflag_f32_e32 v1, v1
	s_nop 0
	v_mul_f32_e32 v1, 0x4f7ffffe, v1
	v_cvt_u32_f32_e32 v1, v1
	s_nop 0
	v_readfirstlane_b32 s5, v1
	s_mul_i32 s3, s3, s5
	s_mul_hi_u32 s3, s5, s3
	s_add_i32 s5, s5, s3
	s_bfe_i32 s3, s4, 0x80000
	s_sext_i32_i16 s3, s3
	s_ashr_i32 s3, s3, 3
	v_writelane_b32 v253, s3, 52
	s_mul_hi_u32 s3, s5, 0x440
	s_mul_i32 s3, s3, s2
	s_sub_i32 s3, 0x440, s3
	s_sub_i32 s4, s3, s2
	s_cmp_ge_u32 s3, s2
	s_cselect_b32 s3, s4, s3
	s_sub_i32 s4, s3, s2
	s_cmp_ge_u32 s3, s2
	s_cselect_b32 s2, s4, s3
	v_writelane_b32 v253, s14, 53
	s_cmp_ge_i32 s97, s2
	s_cselect_b64 s[4:5], -1, 0
	v_writelane_b32 v253, s15, 54
	v_writelane_b32 v253, s4, 55
	s_sub_i32 s3, s97, s2
	s_sub_i32 s2, s95, s2
	v_writelane_b32 v253, s5, 56
	s_lshl_b32 s3, s3, 3
	s_lshl_b32 s2, s2, 3
	v_writelane_b32 v253, s2, 57
	s_add_i32 s2, s3, 0x1580
	v_writelane_b32 v253, s2, 58
	s_lshl_b32 s2, s95, 10
	v_writelane_b32 v253, s2, 59
	v_writelane_b32 v253, s6, 60
	s_add_i32 s2, s6, s96
	v_writelane_b32 v253, s2, 61
	s_lshl_b32 s2, s97, 17
	v_writelane_b32 v253, s2, 62
	s_lshl_b32 s2, s95, 17
	v_writelane_b32 v253, s2, 63
	s_lshl_b32 s2, s97, 14
	v_writelane_b32 v254, s2, 0
	s_lshl_b32 s2, s97, 4
	v_writelane_b32 v254, s2, 1
	s_lshl_b32 s2, s97, 8
	v_writelane_b32 v254, s2, 2
	s_add_i32 s2, 0, 0x25ff0
	v_writelane_b32 v254, s2, 3
	s_add_i32 s2, 0, 0x25ff4
	v_writelane_b32 v254, s2, 4
	s_add_i32 s2, 0, 0x20000
	v_writelane_b32 v254, s2, 5
	s_add_i32 s4, 0, 0x13c00
	v_writelane_b32 v254, s4, 6
	s_add_i32 s4, 0, 0x10800
	v_writelane_b32 v254, s4, 7
	s_add_i32 s4, 0, 0x25ff8
	v_writelane_b32 v254, s4, 8
	s_mov_b32 s5, s13
	v_writelane_b32 v254, s4, 9
	s_ashr_i32 s9, s8, 31
	s_ashr_i32 s11, s10, 31
	v_writelane_b32 v254, s5, 10
	v_writelane_b32 v254, s12, 11
	v_mov_b32_e32 v1, 1
	s_mov_b32 s6, 0xffff0000
	v_writelane_b32 v254, s13, 12
	v_writelane_b32 v254, s8, 13
	s_lshl_b64 s[4:5], s[8:9], 6
	s_mov_b32 s2, 0x78000
	v_writelane_b32 v254, s9, 14
	v_writelane_b32 v254, s4, 15
	s_mov_b32 s3, 0x90000
	s_nop 0
	v_writelane_b32 v254, s5, 16
	s_lshl_b64 s[4:5], s[10:11], 1
	v_writelane_b32 v254, s4, 17
	s_nop 1
	v_writelane_b32 v254, s5, 18
	s_mov_b32 s4, s10
	v_writelane_b32 v254, s4, 19
	s_nop 1
	v_writelane_b32 v254, s5, 20
	s_lshl_b64 s[4:5], s[10:11], 2
	s_load_dwordx16 s[60:75], s[0:1], 0x0
	s_load_dwordx16 s[8:23], s[0:1], 0x40
	v_writelane_b32 v254, s4, 21
	s_nop 1
	v_writelane_b32 v254, s5, 22
	s_waitcnt lgkmcnt(0)
	v_writelane_b32 v254, s8, 23
	s_nop 1
	v_writelane_b32 v254, s9, 24
	v_writelane_b32 v254, s10, 25
	v_writelane_b32 v254, s11, 26
	v_writelane_b32 v254, s12, 27
	v_writelane_b32 v254, s13, 28
	v_writelane_b32 v254, s14, 29
	v_writelane_b32 v254, s15, 30
	v_writelane_b32 v254, s16, 31
	v_writelane_b32 v254, s17, 32
	v_writelane_b32 v254, s18, 33
	v_writelane_b32 v254, s19, 34
	v_writelane_b32 v254, s20, 35
	v_writelane_b32 v254, s21, 36
	v_writelane_b32 v254, s22, 37
	v_writelane_b32 v254, s23, 38
	s_load_dwordx16 s[8:23], s[0:1], 0x80
	s_waitcnt lgkmcnt(0)
	v_writelane_b32 v254, s8, 39
	s_nop 1
	v_writelane_b32 v254, s9, 40
	v_writelane_b32 v254, s10, 41
	v_writelane_b32 v254, s11, 42
	v_writelane_b32 v254, s12, 43
	v_writelane_b32 v254, s13, 44
	v_writelane_b32 v254, s14, 45
	v_writelane_b32 v254, s15, 46
	v_writelane_b32 v254, s16, 47
	v_writelane_b32 v254, s17, 48
	v_writelane_b32 v254, s18, 49
	v_writelane_b32 v254, s19, 50
	v_writelane_b32 v254, s20, 51
	v_writelane_b32 v254, s21, 52
	v_writelane_b32 v254, s22, 53
	v_writelane_b32 v254, s23, 54
	v_writelane_b32 v254, s95, 55
	v_writelane_b32 v254, s96, 56
	v_writelane_b32 v254, s92, 57
	s_nop 1
	v_writelane_b32 v254, s93, 58
	v_writelane_b32 v254, s58, 59
	s_nop 1
	v_writelane_b32 v254, s59, 60
	v_writelane_b32 v254, s94, 61
	v_writelane_b32 v254, s60, 62
	s_nop 1
	v_writelane_b32 v255, s62, 0
	v_writelane_b32 v255, s63, 1
	v_writelane_b32 v255, s64, 2
	v_writelane_b32 v255, s65, 3
	v_writelane_b32 v255, s66, 4
	v_writelane_b32 v255, s67, 5
	v_writelane_b32 v255, s68, 6
	v_writelane_b32 v255, s69, 7
	v_writelane_b32 v255, s70, 8
	v_writelane_b32 v255, s71, 9
	v_writelane_b32 v255, s72, 10
	v_writelane_b32 v255, s73, 11
	v_writelane_b32 v255, s74, 12
	v_writelane_b32 v255, s75, 13
	v_writelane_b32 v255, s28, 14
	v_writelane_b32 v254, s61, 63
	s_nop 0
	v_writelane_b32 v255, s29, 15
	s_branch .LBB0_9

; __device__ __forceinline__ unsigned xb_ld(unsigned* p)              { return __hip_atomic_load(p, __ATOMIC_RELAXED, __HIP_MEMORY_SCOPE_AGENT); }
; __device__ __forceinline__ unsigned xb_add(unsigned* p, unsigned v) { return __hip_atomic_fetch_add(p, v, __ATOMIC_RELAXED, __HIP_MEMORY_SCOPE_AGENT); }
; #define XB_SPIN(cond, bar) do { unsigned _sp = 0; while (cond) { __builtin_amdgcn_s_sleep(1); \
;     if ((++_sp & 255u) == 0u) { if (xb_ld(&(bar)[XB_TMO])) break; if (_sp > XB_SPIN_CAP) { atomicAdd(&(bar)[XB_TMO], 1u); break; } } } } while (0)
; __device__ __forceinline__ void xcd_barrier(const XcdBarrier& b) {
;     ...
;         const unsigned old = xb_add(&bar[XB_XSUB(b.x)], 1u);
;         const unsigned gen = old / nloc;
;         if (old + 1u == (gen + 1u) * nloc) {
;     ...
;         } else {
;             XB_SPIN(xb_ld(&bar[XB_XGEN(b.x)]) == gen, bar);
.LBB0_26:
	v_readlane_b32 s99, v255, 37
	s_add_i32 s34, s99, 1
	s_nop 0
	v_writelane_b32 v255, s34, 37
	s_mov_b64 s[36:37], exec
	v_mbcnt_lo_u32_b32 v3, s36, 0
	v_mbcnt_hi_u32_b32 v3, s37, v3
	v_cmp_eq_u32_e32 vcc, 0, v3
	s_and_saveexec_b64 s[4:5], vcc
	s_cbranch_execz .LBB0_28
	s_bcnt1_i32_b64 s34, s[36:37]
	v_readlane_b32 s28, v252, 22
	v_mov_b32_e32 v5, s34
	v_readlane_b32 s29, v252, 23
	s_nop 4
	global_atomic_add v5, v207, v5, s[28:29] sc0
.LBB0_28:
	s_or_b64 exec, exec, s[4:5]
	s_waitcnt vmcnt(0)
	v_readfirstlane_b32 s4, v5
	s_nop 1
	v_add_u32_e32 v7, s4, v3
	v_mov_b32_e32 v3, s99
	v_add_u32_e32 v5, 1, v7
	v_mul_lo_u32 v6, v4, v3
	v_add_u32_e32 v4, v6, v4
	v_cmp_ne_u32_e32 vcc, v5, v4
	s_and_saveexec_b64 s[4:5], vcc
	s_xor_b64 s[4:5], exec, s[4:5]
	s_cbranch_execz .LBB0_42
	v_readlane_b32 s28, v252, 24
	v_readlane_b32 s29, v252, 25
	s_waitcnt lgkmcnt(0)
	s_nop 3
	global_load_dword v2, v207, s[28:29] sc1
	s_waitcnt vmcnt(0)
	v_cmp_eq_u32_e32 vcc, v2, v3
	s_and_saveexec_b64 s[36:37], vcc
	s_cbranch_execz .LBB0_41
	s_mov_b32 s34, 1
	s_mov_b64 s[38:39], 0
	s_branch .LBB0_32

; __device__ __forceinline__ unsigned xb_ld(unsigned* p)              { return __hip_atomic_load(p, __ATOMIC_RELAXED, __HIP_MEMORY_SCOPE_AGENT); }
; __device__ __forceinline__ unsigned xb_add(unsigned* p, unsigned v) { return __hip_atomic_fetch_add(p, v, __ATOMIC_RELAXED, __HIP_MEMORY_SCOPE_AGENT); }
; #define XB_SPIN(cond, bar) do { unsigned _sp = 0; while (cond) { __builtin_amdgcn_s_sleep(1); \
;     if ((++_sp & 255u) == 0u) { if (xb_ld(&(bar)[XB_TMO])) break; if (_sp > XB_SPIN_CAP) { atomicAdd(&(bar)[XB_TMO], 1u); break; } } } } while (0)
; __device__ __forceinline__ void xcd_barrier(const XcdBarrier& b) {
;     ...
;         const unsigned old = xb_add(&bar[XB_XSUB(b.x)], 1u);
;         const unsigned gen = old / nloc;
;         if (old + 1u == (gen + 1u) * nloc) {
;             __builtin_amdgcn_fence(__ATOMIC_RELEASE, "agent");
;             asm volatile("s_waitcnt vmcnt(0)" ::: "memory");
;             const unsigned og = xb_add(&bar[XB_TOP], 1u);
;             const unsigned tg = og / nx;
;             if (og + 1u == (tg + 1u) * nx) xb_add(&bar[XB_TOPGEN], 1u);
;             else XB_SPIN(xb_ld(&bar[XB_TOPGEN]) == tg, bar);
.LBB0_45:
	s_or_b64 exec, exec, s[36:37]
	s_waitcnt vmcnt(0)
	v_readfirstlane_b32 s4, v4
	s_mov_b64 s[36:37], -1
	s_nop 1
	v_add_u32_e32 v3, s4, v3
	v_add_u32_e32 v6, 1, v3
	v_mov_b32_e32 v4, s98
	v_readlane_b32 s4, v252, 28
	v_readlane_b32 s5, v252, 29
	v_mul_lo_u32 v3, v2, v4
	v_add_u32_e32 v2, v3, v2
	v_cmp_ne_u32_e32 vcc, v6, v2
	v_mov_b64_e32 v[2:3], s[4:5]
	s_and_saveexec_b64 s[4:5], vcc
	s_cbranch_execnz .Lxb_notlast_0
	s_or_b64 exec, exec, s[4:5]
	v_readlane_b32 s28, v252, 26
	v_readlane_b32 s29, v252, 27
	v_mov_b32_e32 v2, 1
	s_add_u32 s28, s28, 0xfffff000
	s_addc_u32 s29, s29, -1
	s_nop 4
	global_atomic_add v207, v2, s[28:29]
	global_atomic_add v207, v2, s[28:29] offset:256
	global_atomic_add v207, v2, s[28:29] offset:512
	global_atomic_add v207, v2, s[28:29] offset:768
	global_atomic_add v207, v2, s[28:29] offset:1024
	global_atomic_add v207, v2, s[28:29] offset:1280
	global_atomic_add v207, v2, s[28:29] offset:1536
	global_atomic_add v207, v2, s[28:29] offset:1792
	global_atomic_add v207, v2, s[28:29] offset:2048
	global_atomic_add v207, v2, s[28:29] offset:2304
	global_atomic_add v207, v2, s[28:29] offset:2560
	global_atomic_add v207, v2, s[28:29] offset:2816
	global_atomic_add v207, v2, s[28:29] offset:3072
	global_atomic_add v207, v2, s[28:29] offset:3328
	global_atomic_add v207, v2, s[28:29] offset:3584
	global_atomic_add v207, v2, s[28:29] offset:3840
	s_branch .LBB0_59

; __device__ __forceinline__ unsigned xb_ld(unsigned* p)              { return __hip_atomic_load(p, __ATOMIC_RELAXED, __HIP_MEMORY_SCOPE_AGENT); }
; __device__ __forceinline__ unsigned xb_add(unsigned* p, unsigned v) { return __hip_atomic_fetch_add(p, v, __ATOMIC_RELAXED, __HIP_MEMORY_SCOPE_AGENT); }
; #define XB_SPIN(cond, bar) do { unsigned _sp = 0; while (cond) { __builtin_amdgcn_s_sleep(1); \
;     if ((++_sp & 255u) == 0u) { if (xb_ld(&(bar)[XB_TMO])) break; if (_sp > XB_SPIN_CAP) { atomicAdd(&(bar)[XB_TMO], 1u); break; } } } } while (0)
; __device__ __forceinline__ void xcd_barrier(const XcdBarrier& b) {
;     ...
;         const unsigned old = xb_add(&bar[XB_XSUB(b.x)], 1u);
;         const unsigned gen = old / nloc;
;         if (old + 1u == (gen + 1u) * nloc) {
;     ...
;         } else {
;             XB_SPIN(xb_ld(&bar[XB_XGEN(b.x)]) == gen, bar);
.LBB0_305:
	v_readlane_b32 s99, v255, 37
	s_add_i32 s34, s99, 1
	s_nop 0
	v_writelane_b32 v255, s34, 37
	s_mov_b64 s[38:39], exec
	v_mbcnt_lo_u32_b32 v3, s38, 0
	v_mbcnt_hi_u32_b32 v3, s39, v3
	v_cmp_eq_u32_e32 vcc, 0, v3
	s_and_saveexec_b64 s[4:5], vcc
	s_cbranch_execz .LBB0_307
	s_bcnt1_i32_b64 s34, s[38:39]
	v_readlane_b32 s28, v252, 22
	v_mov_b32_e32 v5, s34
	v_readlane_b32 s29, v252, 23
	s_nop 4
	global_atomic_add v5, v207, v5, s[28:29] sc0
.LBB0_307:
	s_or_b64 exec, exec, s[4:5]
	s_waitcnt vmcnt(0)
	v_readfirstlane_b32 s4, v5
	s_nop 1
	v_add_u32_e32 v7, s4, v3
	v_mov_b32_e32 v3, s99
	v_add_u32_e32 v5, 1, v7
	v_mul_lo_u32 v6, v4, v3
	v_add_u32_e32 v4, v6, v4
	v_cmp_ne_u32_e32 vcc, v5, v4
	s_and_saveexec_b64 s[4:5], vcc
	s_xor_b64 s[4:5], exec, s[4:5]
	s_cbranch_execz .LBB0_321
	v_readlane_b32 s28, v252, 24
	v_readlane_b32 s29, v252, 25
	s_waitcnt lgkmcnt(0)
	s_nop 3
	global_load_dword v2, v207, s[28:29] sc1
	s_waitcnt vmcnt(0)
	v_cmp_eq_u32_e32 vcc, v2, v3
	s_and_saveexec_b64 s[38:39], vcc
	s_cbranch_execz .LBB0_320
	s_mov_b32 s34, 1
	s_mov_b64 s[40:41], 0
	s_branch .LBB0_311

; __device__ __forceinline__ unsigned xb_ld(unsigned* p)              { return __hip_atomic_load(p, __ATOMIC_RELAXED, __HIP_MEMORY_SCOPE_AGENT); }
; __device__ __forceinline__ unsigned xb_add(unsigned* p, unsigned v) { return __hip_atomic_fetch_add(p, v, __ATOMIC_RELAXED, __HIP_MEMORY_SCOPE_AGENT); }
; #define XB_SPIN(cond, bar) do { unsigned _sp = 0; while (cond) { __builtin_amdgcn_s_sleep(1); \
;     if ((++_sp & 255u) == 0u) { if (xb_ld(&(bar)[XB_TMO])) break; if (_sp > XB_SPIN_CAP) { atomicAdd(&(bar)[XB_TMO], 1u); break; } } } } while (0)
; __device__ __forceinline__ void xcd_barrier(const XcdBarrier& b) {
;     ...
;         const unsigned old = xb_add(&bar[XB_XSUB(b.x)], 1u);
;         const unsigned gen = old / nloc;
;         if (old + 1u == (gen + 1u) * nloc) {
;             __builtin_amdgcn_fence(__ATOMIC_RELEASE, "agent");
;             asm volatile("s_waitcnt vmcnt(0)" ::: "memory");
;             const unsigned og = xb_add(&bar[XB_TOP], 1u);
;             const unsigned tg = og / nx;
;             if (og + 1u == (tg + 1u) * nx) xb_add(&bar[XB_TOPGEN], 1u);
;             else XB_SPIN(xb_ld(&bar[XB_TOPGEN]) == tg, bar);
.LBB0_324:
	s_or_b64 exec, exec, s[38:39]
	s_waitcnt vmcnt(0)
	v_readfirstlane_b32 s4, v4
	s_mov_b64 s[38:39], -1
	s_nop 1
	v_add_u32_e32 v3, s4, v3
	v_add_u32_e32 v6, 1, v3
	v_mov_b32_e32 v4, s98
	v_readlane_b32 s4, v252, 28
	v_readlane_b32 s5, v252, 29
	v_mul_lo_u32 v3, v2, v4
	v_add_u32_e32 v2, v3, v2
	v_cmp_ne_u32_e32 vcc, v6, v2
	v_mov_b64_e32 v[2:3], s[4:5]
	s_and_saveexec_b64 s[4:5], vcc
	s_cbranch_execnz .Lxb_notlast_1
	s_or_b64 exec, exec, s[4:5]
	v_readlane_b32 s28, v252, 26
	v_readlane_b32 s29, v252, 27
	v_mov_b32_e32 v2, 1
	s_add_u32 s28, s28, 0xfffff000
	s_addc_u32 s29, s29, -1
	s_nop 4
	global_atomic_add v207, v2, s[28:29]
	global_atomic_add v207, v2, s[28:29] offset:256
	global_atomic_add v207, v2, s[28:29] offset:512
	global_atomic_add v207, v2, s[28:29] offset:768
	global_atomic_add v207, v2, s[28:29] offset:1024
	global_atomic_add v207, v2, s[28:29] offset:1280
	global_atomic_add v207, v2, s[28:29] offset:1536
	global_atomic_add v207, v2, s[28:29] offset:1792
	global_atomic_add v207, v2, s[28:29] offset:2048
	global_atomic_add v207, v2, s[28:29] offset:2304
	global_atomic_add v207, v2, s[28:29] offset:2560
	global_atomic_add v207, v2, s[28:29] offset:2816
	global_atomic_add v207, v2, s[28:29] offset:3072
	global_atomic_add v207, v2, s[28:29] offset:3328
	global_atomic_add v207, v2, s[28:29] offset:3584
	global_atomic_add v207, v2, s[28:29] offset:3840
	s_branch .LBB0_338
